# SSD gate fused: per-workgroup gate after own SSD units writes y*g and row partial sums; even out-proj GEMM scales accumulators by rstd after the SSD K half; gate phase and one grid barrier skipped
# baseline (speedup 1.0000x reference)
.LBB0_1090:
	v_readlane_b32 s4, v254, 62
	v_readlane_b32 s5, v254, 63
	s_and_b64 vcc, exec, s[4:5]
	s_waitcnt vmcnt(0)
	s_barrier
	s_cbranch_vccnz .LBB0_1124
	v_readlane_b32 s4, v254, 2
	v_readlane_b32 s5, v254, 60
	s_load_dwordx2 s[6:7], s[0:1], 0xa0
	s_add_u32 s14, s26, 0x7100000
	s_addc_u32 s15, s27, 0
	s_add_u32 s16, s26, 0x9100000
	s_addc_u32 s17, s27, 0
	s_add_u32 s18, s26, 0xb100000
	s_addc_u32 s19, s27, 0
	s_add_u32 s20, s26, 0x16100000
	s_addc_u32 s21, s27, 0
	s_add_u32 s22, s26, 0x1bb00000
	s_addc_u32 s23, s27, 0
	s_lshl_b32 s5, s5, 12
	s_waitcnt lgkmcnt(0)
	s_add_u32 s6, s6, s5
	s_addc_u32 s7, s7, 0
	s_cmpk_lt_i32 s4, 0x100
	s_cbranch_scc0 .Lsg_done
.Lsg_bun:
	s_cmpk_lt_i32 s4, 0x80
	s_cbranch_scc0 .Lsg_prompt
	s_lshr_b32 s8, s4, 4
	s_and_b32 s11, s4, 15
	s_lshl_b32 s8, s8, 10
	s_addk_i32 s8, 0x2000
	s_lshl_b32 s10, s11, 6
	v_lshrrev_b32_e32 v1, 3, v179
	v_and_b32_e32 v2, 7, v179
	s_movk_i32 s12, 64
	s_branch .Lsg_go
.Lsg_prompt:
	s_add_i32 s9, s4, 0xffffff80
	s_lshr_b32 s8, s9, 2
	s_lshl_b32 s8, s8, 8
	s_and_b32 s9, s9, 3
	s_lshl_b32 s11, s9, 2
	s_lshl_b32 s10, s11, 6
	v_lshrrev_b32_e32 v1, 5, v179
	v_and_b32_e32 v2, 31, v179
	s_movk_i32 s12, 16
.Lsg_go:
	v_mov_b32_e32 v45, v2
	v_add_u32_e32 v1, s8, v1
	v_lshl_add_u32 v2, v2, 3, s10
	v_lshlrev_b32_e32 v3, 2, v2
	global_load_dwordx4 v[8:11], v3, s[6:7]
	global_load_dwordx4 v[12:15], v3, s[6:7] offset:16
	v_lshlrev_b32_e32 v2, 1, v2
	v_mov_b32_e32 v3, 0
	v_mov_b32_e32 v34, v1
	v_mov_b32_e32 v35, 0
	v_lshlrev_b64 v[4:5], 11, v[34:35]
	v_lshl_add_u64 v[4:5], v[4:5], 0, s[14:15]
	v_lshl_add_u64 v[4:5], v[4:5], 0, v[2:3]
	v_lshlrev_b64 v[6:7], 11, v[34:35]
	v_lshl_add_u64 v[6:7], v[6:7], 0, s[16:17]
	v_lshl_add_u64 v[6:7], v[6:7], 0, v[2:3]
	v_mul_u32_u24_e32 v38, 0x2c00, v1
	v_mov_b32_e32 v39, 0
	v_lshl_add_u64 v[28:29], v[38:39], 0, s[18:19]
	v_lshl_add_u64 v[28:29], v[28:29], 0, v[2:3]
	v_lshlrev_b64 v[30:31], 12, v[34:35]
	v_lshl_add_u64 v[30:31], v[30:31], 0, s[20:21]
	v_lshl_add_u64 v[30:31], v[30:31], 0, v[2:3]
	s_lshl_b32 s13, s11, 2
	s_add_u32 s48, s22, s13
	s_addc_u32 s49, s23, 0
	v_lshlrev_b64 v[32:33], 6, v[34:35]
	v_lshl_add_u64 v[32:33], v[32:33], 0, s[48:49]
	s_lshl_b32 s28, s12, 11
	s_mov_b32 s29, 0
	s_mul_i32 s34, s12, 0x2c00
	s_mov_b32 s35, 0
	s_lshl_b32 s38, s12, 12
	s_mov_b32 s39, 0
	s_lshl_b32 s40, s12, 6
	s_mov_b32 s41, 0
	s_mov_b32 s13, 16
.Lsg_pass:
	global_load_dwordx4 v[16:19], v[4:5], off
	global_load_dwordx4 v[20:23], v[6:7], off
	global_load_dwordx4 v[24:27], v[28:29], off
	v_mov_b32_e32 v40, 0
	s_waitcnt vmcnt(0)
	v_lshlrev_b32_e32 v46, 16, v16
	v_and_b32_e32 v47, 0xffff0000, v16
	v_lshlrev_b32_e32 v48, 16, v20
	v_and_b32_e32 v49, 0xffff0000, v20
	v_lshlrev_b32_e32 v50, 16, v24
	v_and_b32_e32 v51, 0xffff0000, v24
	v_add_f32_e32 v46, v46, v48
	v_add_f32_e32 v47, v47, v49
	v_mul_f32_e32 v52, 0xbfb8aa3b, v50
	v_mul_f32_e32 v53, 0xbfb8aa3b, v51
	v_exp_f32_e32 v52, v52
	v_exp_f32_e32 v53, v53
	s_nop 0
	v_add_f32_e32 v52, 1.0, v52
	v_add_f32_e32 v53, 1.0, v53
	v_rcp_f32_e32 v52, v52
	v_rcp_f32_e32 v53, v53
	s_nop 0
	v_mul_f32_e32 v52, v50, v52
	v_mul_f32_e32 v53, v51, v53
	v_mul_f32_e32 v46, v46, v52
	v_mul_f32_e32 v47, v47, v53
	v_fmac_f32_e32 v40, v46, v46
	v_fmac_f32_e32 v40, v47, v47
	v_mul_f32_e32 v46, v46, v8
	v_mul_f32_e32 v47, v47, v9
	v_cvt_pk_bf16_f32 v54, v46, v47
	v_lshlrev_b32_e32 v46, 16, v17
	v_and_b32_e32 v47, 0xffff0000, v17
	v_lshlrev_b32_e32 v48, 16, v21
	v_and_b32_e32 v49, 0xffff0000, v21
	v_lshlrev_b32_e32 v50, 16, v25
	v_and_b32_e32 v51, 0xffff0000, v25
	v_add_f32_e32 v46, v46, v48
	v_add_f32_e32 v47, v47, v49
	v_mul_f32_e32 v52, 0xbfb8aa3b, v50
	v_mul_f32_e32 v53, 0xbfb8aa3b, v51
	v_exp_f32_e32 v52, v52
	v_exp_f32_e32 v53, v53
	s_nop 0
	v_add_f32_e32 v52, 1.0, v52
	v_add_f32_e32 v53, 1.0, v53
	v_rcp_f32_e32 v52, v52
	v_rcp_f32_e32 v53, v53
	s_nop 0
	v_mul_f32_e32 v52, v50, v52
	v_mul_f32_e32 v53, v51, v53
	v_mul_f32_e32 v46, v46, v52
	v_mul_f32_e32 v47, v47, v53
	v_fmac_f32_e32 v40, v46, v46
	v_fmac_f32_e32 v40, v47, v47
	v_mul_f32_e32 v46, v46, v10
	v_mul_f32_e32 v47, v47, v11
	v_cvt_pk_bf16_f32 v55, v46, v47
	v_lshlrev_b32_e32 v46, 16, v18
	v_and_b32_e32 v47, 0xffff0000, v18
	v_lshlrev_b32_e32 v48, 16, v22
	v_and_b32_e32 v49, 0xffff0000, v22
	v_lshlrev_b32_e32 v50, 16, v26
	v_and_b32_e32 v51, 0xffff0000, v26
	v_add_f32_e32 v46, v46, v48
	v_add_f32_e32 v47, v47, v49
	v_mul_f32_e32 v52, 0xbfb8aa3b, v50
	v_mul_f32_e32 v53, 0xbfb8aa3b, v51
	v_exp_f32_e32 v52, v52
	v_exp_f32_e32 v53, v53
	s_nop 0
	v_add_f32_e32 v52, 1.0, v52
	v_add_f32_e32 v53, 1.0, v53
	v_rcp_f32_e32 v52, v52
	v_rcp_f32_e32 v53, v53
	s_nop 0
	v_mul_f32_e32 v52, v50, v52
	v_mul_f32_e32 v53, v51, v53
	v_mul_f32_e32 v46, v46, v52
	v_mul_f32_e32 v47, v47, v53
	v_fmac_f32_e32 v40, v46, v46
	v_fmac_f32_e32 v40, v47, v47
	v_mul_f32_e32 v46, v46, v12
	v_mul_f32_e32 v47, v47, v13
	v_cvt_pk_bf16_f32 v56, v46, v47
	v_lshlrev_b32_e32 v46, 16, v19
	v_and_b32_e32 v47, 0xffff0000, v19
	v_lshlrev_b32_e32 v48, 16, v23
	v_and_b32_e32 v49, 0xffff0000, v23
	v_lshlrev_b32_e32 v50, 16, v27
	v_and_b32_e32 v51, 0xffff0000, v27
	v_add_f32_e32 v46, v46, v48
	v_add_f32_e32 v47, v47, v49
	v_mul_f32_e32 v52, 0xbfb8aa3b, v50
	v_mul_f32_e32 v53, 0xbfb8aa3b, v51
	v_exp_f32_e32 v52, v52
	v_exp_f32_e32 v53, v53
	s_nop 0
	v_add_f32_e32 v52, 1.0, v52
	v_add_f32_e32 v53, 1.0, v53
	v_rcp_f32_e32 v52, v52
	v_rcp_f32_e32 v53, v53
	s_nop 0
	v_mul_f32_e32 v52, v50, v52
	v_mul_f32_e32 v53, v51, v53
	v_mul_f32_e32 v46, v46, v52
	v_mul_f32_e32 v47, v47, v53
	v_fmac_f32_e32 v40, v46, v46
	v_fmac_f32_e32 v40, v47, v47
	v_mul_f32_e32 v46, v46, v14
	v_mul_f32_e32 v47, v47, v15
	v_cvt_pk_bf16_f32 v57, v46, v47
	global_store_dwordx4 v[30:31], v[54:57], off
	s_nop 1
	v_add_f32_dpp v40, v40, v40 quad_perm:[1,0,3,2] row_mask:0xf bank_mask:0xf bound_ctrl:1
	s_nop 1
	v_add_f32_dpp v40, v40, v40 quad_perm:[2,3,0,1] row_mask:0xf bank_mask:0xf bound_ctrl:1
	s_nop 1
	v_add_f32_dpp v40, v40, v40 row_half_mirror row_mask:0xf bank_mask:0xf bound_ctrl:1
	s_cmp_eq_u32 s12, 64
	s_cbranch_scc1 .Lsg_red_done
	s_nop 1
	v_add_f32_dpp v40, v40, v40 row_mirror row_mask:0xf bank_mask:0xf bound_ctrl:1
	v_mov_b32_e32 v58, v40
	s_nop 1
	v_permlane16_swap_b32_e32 v40, v58
	v_add_f32_e32 v40, v40, v58
.Lsg_red_done:
	v_mov_b32_e32 v41, 0
	v_mov_b32_e32 v42, 0
	v_mov_b32_e32 v43, 0
	v_cmp_eq_u32_e32 vcc, 0, v45
	s_and_saveexec_b64 s[42:43], vcc
	s_cmp_eq_u32 s12, 64
	s_cbranch_scc0 .Lsg_st4
	global_store_dword v[32:33], v40, off
	s_branch .Lsg_st_done
.Lsg_st4:
	global_store_dwordx4 v[32:33], v[40:43], off
.Lsg_st_done:
	s_or_b64 exec, exec, s[42:43]
	v_lshl_add_u64 v[4:5], v[4:5], 0, s[28:29]
	v_lshl_add_u64 v[6:7], v[6:7], 0, s[28:29]
	v_lshl_add_u64 v[28:29], v[28:29], 0, s[34:35]
	v_lshl_add_u64 v[30:31], v[30:31], 0, s[38:39]
	v_lshl_add_u64 v[32:33], v[32:33], 0, s[40:41]
	s_add_i32 s13, s13, -1
	s_cmp_lg_u32 s13, 0
	s_cbranch_scc1 .Lsg_pass
	s_add_i32 s4, s4, s74
	s_cmpk_lt_i32 s4, 0x100
	s_cbranch_scc1 .Lsg_bun
.Lsg_done:
	v_readlane_b32 s4, v254, 59
	s_cmp_eq_u32 s4, 0
	s_cselect_b64 vcc, -1, 0
	v_mov_b32_e32 v1, 0x3ef1014c
	v_mov_b32_e32 v2, 0x3e4ccccd
	v_readlane_b32 s4, v254, 60
	v_cndmask_b32_e32 v146, v1, v2, vcc
	s_lshl_b32 s62, s4, 8
	s_lshl_b32 s6, s4, 7
	s_mov_b32 s7, s63
	v_sub_f32_e32 v147, 1.0, v146
	s_lshl_b64 s[8:9], s[62:63], 2
	v_readlane_b32 s48, v254, 32
	v_readlane_b32 s49, v254, 2
	v_readlane_b32 s5, v254, 61
	s_branch .LBB0_1093

.LBB0_1124:
	s_mov_b64 s[6:7], s[26:27]
	s_getreg_b32 s8, hwreg(HW_REG_XCC_ID, 0, 4)
	s_waitcnt vmcnt(0)
	s_barrier
	s_mov_b64 s[4:5], exec
	v_readlane_b32 s10, v254, 0
	v_readlane_b32 s11, v254, 1
	v_readlane_b32 s40, v254, 34
	s_mov_b64 s[10:11], 0
	v_readlane_b32 s41, v254, 35
	s_mov_b64 exec, s[10:11]
	s_cbranch_execz .LBB0_1177
	v_readlane_b32 s9, v254, 36
	s_waitcnt vmcnt(0) expcnt(0) lgkmcnt(0)
	s_and_b32 s18, s8, 15
	v_mov_b32_e32 v1, s9
	ds_read_b32 v3, v1
	v_readlane_b32 s9, v254, 37
	s_waitcnt lgkmcnt(0)
	v_cmp_ne_u32_e32 vcc, 0, v3
	v_mov_b32_e32 v1, s9
	ds_read_b32 v2, v1
	s_cbranch_vccnz .LBB0_1141
	s_add_u32 s8, s6, 0x10200
	s_addc_u32 s9, s7, 0
	s_add_u32 s10, s6, 0x10400
	s_addc_u32 s11, s7, 0
	s_add_u32 s12, s6, 0x10500
	s_addc_u32 s13, s7, 0
	s_add_u32 s14, s6, 0x10600
	s_addc_u32 s15, s7, 0
	s_add_u32 s16, s6, 0x10700
	s_addc_u32 s17, s7, 0
	s_add_u32 s20, s6, 0x10800
	s_addc_u32 s21, s7, 0
	s_add_u32 s22, s6, 0x10900
	s_addc_u32 s23, s7, 0
	s_add_u32 s28, s6, 0x10a00
	s_addc_u32 s29, s7, 0
	s_add_u32 s34, s6, 0x10b00
	s_addc_u32 s35, s7, 0
	s_add_u32 s38, s6, 0x10c00
	s_addc_u32 s39, s7, 0
	s_add_u32 s40, s6, 0x10d00
	s_addc_u32 s41, s7, 0
	s_add_u32 s42, s6, 0x10e00
	s_addc_u32 s43, s7, 0
	s_add_u32 s48, s6, 0x10f00
	s_addc_u32 s49, s7, 0
	s_add_u32 s50, s6, 0x11000
	s_addc_u32 s51, s7, 0
	s_add_u32 s52, s6, 0x11100
	s_addc_u32 s53, s7, 0
	s_add_u32 s56, s6, 0x11200
	s_addc_u32 s57, s7, 0
	s_add_u32 s58, s6, 0x11300
	s_addc_u32 s59, s7, 0
	s_mov_b32 s19, 1
	s_branch .LBB0_1129

.LBB0_1177:
	s_or_b64 exec, exec, s[4:5]
	s_mov_b64 s[6:7], s[26:27]
	s_mov_b64 s[8:9], s[26:27]
	s_mov_b64 s[10:11], s[26:27]
	s_mov_b32 s14, 20
	s_mov_b64 s[12:13], s[26:27]
	v_mov_b32_e32 v1, v179
	s_waitcnt lgkmcnt(0)
	s_barrier
	v_readlane_b32 s4, v254, 4
	v_ashrrev_i32_e32 v2, 6, v1
	s_waitcnt vmcnt(4)
	v_add_u32_e32 v34, s4, v2
	s_movk_i32 s4, 0x4000
	s_mov_b64 vcc, 0
	s_and_saveexec_b64 s[4:5], vcc
	v_readlane_b32 s20, v254, 9
	v_readlane_b32 s22, v254, 55
	v_readlane_b32 s18, v254, 53
	v_readlane_b32 s58, v254, 6
	v_readlane_b32 s21, v254, 10
	v_readlane_b32 s23, v254, 56
	s_mov_b32 s49, 0x200000
	s_mov_b64 s[56:57], 0x200000
	v_readlane_b32 s19, v254, 54
	v_readlane_b32 s59, v254, 7
	s_cbranch_execz .LBB0_1180
	s_ashr_i32 s15, s14, 31
	s_lshl_b64 s[14:15], s[14:15], 3
	s_add_u32 s14, s0, s14
	s_addc_u32 s15, s1, s15
	s_load_dwordx2 s[14:15], s[14:15], 0x0
	v_readlane_b32 s16, v254, 60
	v_readlane_b32 s17, v254, 61
	s_lshl_b32 s62, s16, 10
	s_lshl_b64 s[16:17], s[62:63], 2
	v_lshlrev_b32_e32 v2, 5, v1
	s_waitcnt lgkmcnt(0)
	s_add_u32 s14, s14, s16
	v_and_b32_e32 v2, 0x7e0, v2
	s_addc_u32 s15, s15, s17
	v_mov_b32_e32 v3, v0
	v_ashrrev_i32_e32 v35, 31, v34
	v_lshl_add_u64 v[36:37], s[14:15], 0, v[2:3]
	v_lshlrev_b64 v[2:3], 12, v[34:35]
	v_lshl_add_u64 v[40:41], s[12:13], 0, v[2:3]
	v_mov_b64_e32 v[2:3], s[10:11]
	v_and_b32_e32 v1, 63, v1
	v_mad_i64_i32 v[42:43], s[10:11], v34, s3, v[2:3]
	v_lshlrev_b64 v[2:3], 11, v[34:35]
	v_lshlrev_b32_e32 v38, 4, v1
	v_mov_b32_e32 v39, v0
	v_lshl_add_u64 v[44:45], s[8:9], 0, v[2:3]
	v_lshl_add_u64 v[46:47], s[6:7], 0, v[2:3]
	s_mov_b64 s[6:7], 0

.LBB0_1245:
	s_add_u32 s28, s22, 0xfff80080
	s_addc_u32 s29, s23, -1
	s_add_i32 s71, 0, 0x10000
	s_cmp_eq_u32 s70, 28
	s_cselect_b32 s35, s17, s29
	s_cselect_b32 s34, s66, s28
	s_cselect_b32 s29, s15, s69
	s_cselect_b32 s28, s67, s68
	s_add_i32 s76, 0, 0x14000
	v_add_u32_e32 v106, s71, v220
	v_add_u32_e32 v158, s76, v220
	ds_read_b128 v[90:93], v106
	ds_read_b128 v[94:97], v106 offset:1024
	ds_read_b128 v[98:101], v106 offset:2048
	ds_read_b128 v[106:109], v106 offset:3072
	ds_read_b128 v[146:149], v158
	ds_read_b128 v[150:153], v158 offset:1024
	ds_read_b128 v[154:157], v158 offset:2048
	ds_read_b128 v[158:161], v158 offset:3072
	v_lshl_add_u64 v[214:215], s[22:23], 0, v[190:191]
	s_add_i32 m0, s48, 0xc000
	ds_read_b128 v[162:165], v221
	ds_read_b128 v[166:169], v221 offset:1024
	ds_read_b128 v[184:187], v221 offset:2048
	ds_read_b128 v[194:197], v221 offset:3072
	ds_read_b128 v[198:201], v221 offset:4096
	ds_read_b128 v[202:205], v221 offset:5120
	ds_read_b128 v[206:209], v221 offset:6144
	ds_read_b128 v[210:213], v221 offset:7168
	global_load_lds_dwordx4 v[214:215], off
	v_lshl_add_u64 v[214:215], s[22:23], 0, v[192:193]
	s_add_i32 m0, s48, 0xe000
	s_nop 0
	global_load_lds_dwordx4 v[214:215], off
	s_waitcnt vmcnt(8)
	s_waitcnt lgkmcnt(0)
	s_barrier
	s_setprio 1
	s_waitcnt lgkmcnt(0)
	v_mfma_f32_16x16x32_bf16 v[142:145], v[90:93], v[162:165], v[142:145]
	v_mfma_f32_16x16x32_bf16 v[138:141], v[98:101], v[162:165], v[138:141]
	v_mfma_f32_16x16x32_bf16 v[126:129], v[90:93], v[184:187], v[126:129]
	v_mfma_f32_16x16x32_bf16 v[122:125], v[98:101], v[184:187], v[122:125]
	v_mfma_f32_16x16x32_bf16 v[110:113], v[90:93], v[198:201], v[110:113]
	v_mfma_f32_16x16x32_bf16 v[102:105], v[98:101], v[198:201], v[102:105]
	v_mfma_f32_16x16x32_bf16 v[78:81], v[90:93], v[206:209], v[78:81]
	v_mfma_f32_16x16x32_bf16 v[74:77], v[98:101], v[206:209], v[74:77]
	v_mfma_f32_16x16x32_bf16 v[142:145], v[94:97], v[166:169], v[142:145]
	v_mfma_f32_16x16x32_bf16 v[138:141], v[106:109], v[166:169], v[138:141]
	v_mfma_f32_16x16x32_bf16 v[126:129], v[94:97], v[194:197], v[126:129]
	v_mfma_f32_16x16x32_bf16 v[122:125], v[106:109], v[194:197], v[122:125]
	v_mfma_f32_16x16x32_bf16 v[110:113], v[94:97], v[202:205], v[110:113]
	v_mfma_f32_16x16x32_bf16 v[102:105], v[106:109], v[202:205], v[102:105]
	v_mfma_f32_16x16x32_bf16 v[78:81], v[94:97], v[210:213], v[78:81]
	v_mfma_f32_16x16x32_bf16 v[74:77], v[106:109], v[210:213], v[74:77]
	s_setprio 0
	s_setprio 1
	v_mfma_f32_16x16x32_bf16 v[134:137], v[146:149], v[162:165], v[134:137]
	v_mfma_f32_16x16x32_bf16 v[130:133], v[154:157], v[162:165], v[130:133]
	v_mfma_f32_16x16x32_bf16 v[118:121], v[146:149], v[184:187], v[118:121]
	v_mfma_f32_16x16x32_bf16 v[114:117], v[154:157], v[184:187], v[114:117]
	v_mfma_f32_16x16x32_bf16 v[86:89], v[146:149], v[198:201], v[86:89]
	v_mfma_f32_16x16x32_bf16 v[82:85], v[154:157], v[198:201], v[82:85]
	v_mfma_f32_16x16x32_bf16 v[70:73], v[146:149], v[206:209], v[70:73]
	v_mfma_f32_16x16x32_bf16 v[66:69], v[154:157], v[206:209], v[66:69]
	v_mfma_f32_16x16x32_bf16 v[134:137], v[150:153], v[166:169], v[134:137]
	v_mfma_f32_16x16x32_bf16 v[130:133], v[158:161], v[166:169], v[130:133]
	v_mfma_f32_16x16x32_bf16 v[118:121], v[150:153], v[194:197], v[118:121]
	v_mfma_f32_16x16x32_bf16 v[114:117], v[158:161], v[194:197], v[114:117]
	v_mfma_f32_16x16x32_bf16 v[86:89], v[150:153], v[202:205], v[86:89]
	v_mfma_f32_16x16x32_bf16 v[82:85], v[158:161], v[202:205], v[82:85]
	v_mfma_f32_16x16x32_bf16 v[70:73], v[150:153], v[210:213], v[70:73]
	v_mfma_f32_16x16x32_bf16 v[66:69], v[158:161], v[210:213], v[66:69]
	s_setprio 0
	s_barrier
	s_add_i32 s71, s71, s43
	v_lshl_add_u64 v[214:215], s[28:29], 0, v[174:175]
	s_mov_b32 m0, s71
	ds_read_b128 v[162:165], v221 offset:16384
	ds_read_b128 v[166:169], v221 offset:17408
	ds_read_b128 v[184:187], v221 offset:18432
	ds_read_b128 v[194:197], v221 offset:19456
	ds_read_b128 v[198:201], v221 offset:20480
	ds_read_b128 v[202:205], v221 offset:21504
	ds_read_b128 v[206:209], v221 offset:22528
	ds_read_b128 v[210:213], v221 offset:23552
	global_load_lds_dwordx4 v[214:215], off
	s_add_i32 m0, s71, 0x2000
	s_add_u32 s74, s28, 0x80000
	v_lshl_add_u64 v[216:217], s[28:29], 0, v[170:171]
	s_addc_u32 s75, s29, 0
	s_add_i32 s71, s76, s43
	global_load_lds_dwordx4 v[216:217], off
	v_lshl_add_u64 v[218:219], s[74:75], 0, v[174:175]
	s_mov_b32 m0, s71
	v_lshl_add_u64 v[222:223], s[34:35], 0, v[172:173]
	global_load_lds_dwordx4 v[218:219], off
	v_lshl_add_u64 v[218:219], s[74:75], 0, v[170:171]
	s_add_i32 m0, s71, 0x2000
	s_nop 0
	global_load_lds_dwordx4 v[218:219], off
	v_lshl_add_u64 v[218:219], s[34:35], 0, v[176:177]
	s_mov_b32 m0, s48
	s_nop 0
	global_load_lds_dwordx4 v[218:219], off
	s_mov_b32 m0, s49
	s_nop 0
	global_load_lds_dwordx4 v[222:223], off
	s_waitcnt vmcnt(8)
	s_waitcnt lgkmcnt(0)
	s_barrier
	s_setprio 1
	s_waitcnt lgkmcnt(0)
	v_mfma_f32_16x16x32_bf16 v[62:65], v[90:93], v[162:165], v[62:65]
	v_mfma_f32_16x16x32_bf16 v[58:61], v[98:101], v[162:165], v[58:61]
	v_mfma_f32_16x16x32_bf16 v[46:49], v[90:93], v[184:187], v[46:49]
	v_mfma_f32_16x16x32_bf16 v[42:45], v[98:101], v[184:187], v[42:45]
	v_mfma_f32_16x16x32_bf16 v[30:33], v[90:93], v[198:201], v[30:33]
	v_mfma_f32_16x16x32_bf16 v[26:29], v[98:101], v[198:201], v[26:29]
	v_mfma_f32_16x16x32_bf16 v[14:17], v[90:93], v[206:209], v[14:17]
	v_mfma_f32_16x16x32_bf16 v[10:13], v[98:101], v[206:209], v[10:13]
	v_mfma_f32_16x16x32_bf16 v[62:65], v[94:97], v[166:169], v[62:65]
	v_mfma_f32_16x16x32_bf16 v[58:61], v[106:109], v[166:169], v[58:61]
	v_mfma_f32_16x16x32_bf16 v[46:49], v[94:97], v[194:197], v[46:49]
	v_mfma_f32_16x16x32_bf16 v[42:45], v[106:109], v[194:197], v[42:45]
	v_mfma_f32_16x16x32_bf16 v[30:33], v[94:97], v[202:205], v[30:33]
	v_mfma_f32_16x16x32_bf16 v[26:29], v[106:109], v[202:205], v[26:29]
	v_mfma_f32_16x16x32_bf16 v[14:17], v[94:97], v[210:213], v[14:17]
	v_mfma_f32_16x16x32_bf16 v[10:13], v[106:109], v[210:213], v[10:13]
	s_setprio 0
	s_setprio 1
	v_mfma_f32_16x16x32_bf16 v[54:57], v[146:149], v[162:165], v[54:57]
	v_mfma_f32_16x16x32_bf16 v[50:53], v[154:157], v[162:165], v[50:53]
	v_mfma_f32_16x16x32_bf16 v[38:41], v[146:149], v[184:187], v[38:41]
	v_mfma_f32_16x16x32_bf16 v[34:37], v[154:157], v[184:187], v[34:37]
	v_mfma_f32_16x16x32_bf16 v[22:25], v[146:149], v[198:201], v[22:25]
	v_mfma_f32_16x16x32_bf16 v[18:21], v[154:157], v[198:201], v[18:21]
	v_mfma_f32_16x16x32_bf16 v[6:9], v[146:149], v[206:209], v[6:9]
	v_mfma_f32_16x16x32_bf16 v[2:5], v[154:157], v[206:209], v[2:5]
	v_mfma_f32_16x16x32_bf16 v[54:57], v[150:153], v[166:169], v[54:57]
	v_mfma_f32_16x16x32_bf16 v[50:53], v[158:161], v[166:169], v[50:53]
	v_mfma_f32_16x16x32_bf16 v[38:41], v[150:153], v[194:197], v[38:41]
	v_mfma_f32_16x16x32_bf16 v[34:37], v[158:161], v[194:197], v[34:37]
	v_mfma_f32_16x16x32_bf16 v[22:25], v[150:153], v[202:205], v[22:25]
	v_mfma_f32_16x16x32_bf16 v[18:21], v[158:161], v[202:205], v[18:21]
	v_mfma_f32_16x16x32_bf16 v[6:9], v[150:153], v[210:213], v[6:9]
	v_mfma_f32_16x16x32_bf16 v[2:5], v[158:161], v[210:213], v[2:5]
	s_setprio 0
	s_barrier
	s_add_i32 s71, 0, 0x18000
	s_add_i32 s74, 0, 0x1c000
	v_add_u32_e32 v106, s71, v220
	v_add_u32_e32 v158, s74, v220
	ds_read_b128 v[90:93], v106
	ds_read_b128 v[94:97], v106 offset:1024
	ds_read_b128 v[98:101], v106 offset:2048
	ds_read_b128 v[106:109], v106 offset:3072
	ds_read_b128 v[146:149], v158
	ds_read_b128 v[150:153], v158 offset:1024
	ds_read_b128 v[154:157], v158 offset:2048
	ds_read_b128 v[158:161], v158 offset:3072
	s_add_u32 s34, s34, 0x80000
	s_addc_u32 s35, s35, 0
	s_mov_b32 m0, s50
	v_lshl_add_u64 v[224:225], s[34:35], 0, v[176:177]
	ds_read_b128 v[162:165], v221 offset:32768
	ds_read_b128 v[166:169], v221 offset:33792
	ds_read_b128 v[184:187], v221 offset:34816
	ds_read_b128 v[194:197], v221 offset:35840
	ds_read_b128 v[198:201], v221 offset:36864
	ds_read_b128 v[202:205], v221 offset:37888
	ds_read_b128 v[206:209], v221 offset:38912
	ds_read_b128 v[210:213], v221 offset:39936
	global_load_lds_dwordx4 v[224:225], off
	v_lshl_add_u64 v[224:225], s[34:35], 0, v[172:173]
	s_mov_b32 m0, s51
	s_nop 0
	global_load_lds_dwordx4 v[224:225], off
	s_waitcnt vmcnt(8)
	s_waitcnt lgkmcnt(0)
	s_barrier
	s_setprio 1
	s_waitcnt lgkmcnt(0)
	v_mfma_f32_16x16x32_bf16 v[142:145], v[90:93], v[162:165], v[142:145]
	v_mfma_f32_16x16x32_bf16 v[138:141], v[98:101], v[162:165], v[138:141]
	v_mfma_f32_16x16x32_bf16 v[126:129], v[90:93], v[184:187], v[126:129]
	v_mfma_f32_16x16x32_bf16 v[122:125], v[98:101], v[184:187], v[122:125]
	v_mfma_f32_16x16x32_bf16 v[110:113], v[90:93], v[198:201], v[110:113]
	v_mfma_f32_16x16x32_bf16 v[102:105], v[98:101], v[198:201], v[102:105]
	v_mfma_f32_16x16x32_bf16 v[78:81], v[90:93], v[206:209], v[78:81]
	v_mfma_f32_16x16x32_bf16 v[74:77], v[98:101], v[206:209], v[74:77]
	v_mfma_f32_16x16x32_bf16 v[142:145], v[94:97], v[166:169], v[142:145]
	v_mfma_f32_16x16x32_bf16 v[138:141], v[106:109], v[166:169], v[138:141]
	v_mfma_f32_16x16x32_bf16 v[126:129], v[94:97], v[194:197], v[126:129]
	v_mfma_f32_16x16x32_bf16 v[122:125], v[106:109], v[194:197], v[122:125]
	v_mfma_f32_16x16x32_bf16 v[110:113], v[94:97], v[202:205], v[110:113]
	v_mfma_f32_16x16x32_bf16 v[102:105], v[106:109], v[202:205], v[102:105]
	v_mfma_f32_16x16x32_bf16 v[78:81], v[94:97], v[210:213], v[78:81]
	v_mfma_f32_16x16x32_bf16 v[74:77], v[106:109], v[210:213], v[74:77]
	s_setprio 0
	s_setprio 1
	v_mfma_f32_16x16x32_bf16 v[134:137], v[146:149], v[162:165], v[134:137]
	v_mfma_f32_16x16x32_bf16 v[130:133], v[154:157], v[162:165], v[130:133]
	v_mfma_f32_16x16x32_bf16 v[118:121], v[146:149], v[184:187], v[118:121]
	v_mfma_f32_16x16x32_bf16 v[114:117], v[154:157], v[184:187], v[114:117]
	v_mfma_f32_16x16x32_bf16 v[86:89], v[146:149], v[198:201], v[86:89]
	v_mfma_f32_16x16x32_bf16 v[82:85], v[154:157], v[198:201], v[82:85]
	v_mfma_f32_16x16x32_bf16 v[70:73], v[146:149], v[206:209], v[70:73]
	v_mfma_f32_16x16x32_bf16 v[66:69], v[154:157], v[206:209], v[66:69]
	v_mfma_f32_16x16x32_bf16 v[134:137], v[150:153], v[166:169], v[134:137]
	v_mfma_f32_16x16x32_bf16 v[130:133], v[158:161], v[166:169], v[130:133]
	v_mfma_f32_16x16x32_bf16 v[118:121], v[150:153], v[194:197], v[118:121]
	v_mfma_f32_16x16x32_bf16 v[114:117], v[158:161], v[194:197], v[114:117]
	v_mfma_f32_16x16x32_bf16 v[86:89], v[150:153], v[202:205], v[86:89]
	v_mfma_f32_16x16x32_bf16 v[82:85], v[158:161], v[202:205], v[82:85]
	v_mfma_f32_16x16x32_bf16 v[70:73], v[150:153], v[210:213], v[70:73]
	v_mfma_f32_16x16x32_bf16 v[66:69], v[158:161], v[210:213], v[66:69]
	s_setprio 0
	s_barrier
	s_add_i32 s34, s71, s43
	v_lshl_add_u64 v[214:215], v[214:215], 0, s[72:73]
	s_mov_b32 m0, s34
	ds_read_b128 v[162:165], v221 offset:49152
	ds_read_b128 v[166:169], v221 offset:50176
	ds_read_b128 v[184:187], v221 offset:51200
	ds_read_b128 v[194:197], v221 offset:52224
	ds_read_b128 v[198:201], v221 offset:53248
	ds_read_b128 v[202:205], v221 offset:54272
	ds_read_b128 v[206:209], v221 offset:55296
	ds_read_b128 v[210:213], v221 offset:56320
	global_load_lds_dwordx4 v[214:215], off
	s_add_i32 m0, s34, 0x2000
	s_add_u32 s28, s28, 0x80080
	v_lshl_add_u64 v[214:215], v[216:217], 0, s[72:73]
	s_addc_u32 s29, s29, 0
	s_add_i32 s34, s74, s43
	global_load_lds_dwordx4 v[214:215], off
	v_lshl_add_u64 v[214:215], s[28:29], 0, v[174:175]
	s_mov_b32 m0, s34
	s_nop 0
	global_load_lds_dwordx4 v[214:215], off
	v_lshl_add_u64 v[214:215], s[28:29], 0, v[170:171]
	s_add_i32 m0, s34, 0x2000
	s_nop 0
	global_load_lds_dwordx4 v[214:215], off
	v_lshl_add_u64 v[214:215], v[218:219], 0, s[72:73]
	s_mov_b32 m0, s60
	s_nop 0
	global_load_lds_dwordx4 v[214:215], off
	v_lshl_add_u64 v[214:215], v[222:223], 0, s[72:73]
	s_mov_b32 m0, s61
	s_nop 0
	global_load_lds_dwordx4 v[214:215], off
	s_waitcnt vmcnt(8)
	s_waitcnt lgkmcnt(0)
	s_barrier
	s_setprio 1
	s_waitcnt lgkmcnt(0)
	v_mfma_f32_16x16x32_bf16 v[62:65], v[90:93], v[162:165], v[62:65]
	v_mfma_f32_16x16x32_bf16 v[58:61], v[98:101], v[162:165], v[58:61]
	v_mfma_f32_16x16x32_bf16 v[46:49], v[90:93], v[184:187], v[46:49]
	v_mfma_f32_16x16x32_bf16 v[42:45], v[98:101], v[184:187], v[42:45]
	v_mfma_f32_16x16x32_bf16 v[30:33], v[90:93], v[198:201], v[30:33]
	v_mfma_f32_16x16x32_bf16 v[26:29], v[98:101], v[198:201], v[26:29]
	v_mfma_f32_16x16x32_bf16 v[14:17], v[90:93], v[206:209], v[14:17]
	v_mfma_f32_16x16x32_bf16 v[10:13], v[98:101], v[206:209], v[10:13]
	v_mfma_f32_16x16x32_bf16 v[62:65], v[94:97], v[166:169], v[62:65]
	v_mfma_f32_16x16x32_bf16 v[58:61], v[106:109], v[166:169], v[58:61]
	v_mfma_f32_16x16x32_bf16 v[46:49], v[94:97], v[194:197], v[46:49]
	v_mfma_f32_16x16x32_bf16 v[42:45], v[106:109], v[194:197], v[42:45]
	v_mfma_f32_16x16x32_bf16 v[30:33], v[94:97], v[202:205], v[30:33]
	v_mfma_f32_16x16x32_bf16 v[26:29], v[106:109], v[202:205], v[26:29]
	v_mfma_f32_16x16x32_bf16 v[14:17], v[94:97], v[210:213], v[14:17]
	v_mfma_f32_16x16x32_bf16 v[10:13], v[106:109], v[210:213], v[10:13]
	s_setprio 0
	s_setprio 1
	v_mfma_f32_16x16x32_bf16 v[54:57], v[146:149], v[162:165], v[54:57]
	v_mfma_f32_16x16x32_bf16 v[50:53], v[154:157], v[162:165], v[50:53]
	v_mfma_f32_16x16x32_bf16 v[38:41], v[146:149], v[184:187], v[38:41]
	v_mfma_f32_16x16x32_bf16 v[34:37], v[154:157], v[184:187], v[34:37]
	v_mfma_f32_16x16x32_bf16 v[22:25], v[146:149], v[198:201], v[22:25]
	v_mfma_f32_16x16x32_bf16 v[18:21], v[154:157], v[198:201], v[18:21]
	v_mfma_f32_16x16x32_bf16 v[6:9], v[146:149], v[206:209], v[6:9]
	v_mfma_f32_16x16x32_bf16 v[2:5], v[154:157], v[206:209], v[2:5]
	v_mfma_f32_16x16x32_bf16 v[54:57], v[150:153], v[166:169], v[54:57]
	v_mfma_f32_16x16x32_bf16 v[50:53], v[158:161], v[166:169], v[50:53]
	v_mfma_f32_16x16x32_bf16 v[38:41], v[150:153], v[194:197], v[38:41]
	v_mfma_f32_16x16x32_bf16 v[34:37], v[158:161], v[194:197], v[34:37]
	v_mfma_f32_16x16x32_bf16 v[22:25], v[150:153], v[202:205], v[22:25]
	v_mfma_f32_16x16x32_bf16 v[18:21], v[158:161], v[202:205], v[18:21]
	v_mfma_f32_16x16x32_bf16 v[6:9], v[150:153], v[210:213], v[6:9]
	v_mfma_f32_16x16x32_bf16 v[2:5], v[158:161], v[210:213], v[2:5]
	s_setprio 0
	s_barrier
	s_add_i32 s70, s70, 2
	s_add_u32 s22, s22, 0x100
	s_addc_u32 s23, s23, 0
	s_add_u32 s68, s68, 0x100
	s_addc_u32 s69, s69, 0
	s_cmp_lg_u32 s70, 14
	s_cbranch_scc1 .Lssd_noscale
	s_lshl_b32 s28, s65, 8
	s_add_i32 s28, s28, s58
	v_add_u32_e32 v146, s28, v189
	v_lshlrev_b32_e32 v146, 6, v146
	v_lshl_add_u32 v146, v1, 4, v146
	v_mov_b32_e32 v147, 0
	s_add_u32 s28, s26, 0x1bb00000
	s_addc_u32 s29, s27, 0
	v_lshl_add_u64 v[146:147], s[28:29], 0, v[146:147]
	global_load_dwordx4 v[148:151], v[146:147], off
	global_load_dwordx4 v[152:155], v[146:147], off offset:1024
	global_load_dwordx4 v[156:159], v[146:147], off offset:2048
	global_load_dwordx4 v[160:163], v[146:147], off offset:3072
	s_mov_b64 s[28:29], 0x2000
	v_lshl_add_u64 v[146:147], v[146:147], 0, s[28:29]
	global_load_dwordx4 v[164:167], v[146:147], off
	global_load_dwordx4 v[194:197], v[146:147], off offset:1024
	global_load_dwordx4 v[198:201], v[146:147], off offset:2048
	global_load_dwordx4 v[202:205], v[146:147], off offset:3072
	v_mov_b32_e32 v206, 0x358637bd
	s_waitcnt vmcnt(0)
	v_add_f32_e32 v148, v148, v149
	v_add_f32_e32 v150, v150, v151
	v_add_f32_e32 v148, v148, v150
	v_add_f32_e32 v152, v152, v153
	v_add_f32_e32 v154, v154, v155
	v_add_f32_e32 v152, v152, v154
	v_add_f32_e32 v156, v156, v157
	v_add_f32_e32 v158, v158, v159
	v_add_f32_e32 v156, v156, v158
	v_add_f32_e32 v160, v160, v161
	v_add_f32_e32 v162, v162, v163
	v_add_f32_e32 v160, v160, v162
	v_add_f32_e32 v164, v164, v165
	v_add_f32_e32 v166, v166, v167
	v_add_f32_e32 v164, v164, v166
	v_add_f32_e32 v194, v194, v195
	v_add_f32_e32 v196, v196, v197
	v_add_f32_e32 v194, v194, v196
	v_add_f32_e32 v198, v198, v199
	v_add_f32_e32 v200, v200, v201
	v_add_f32_e32 v198, v198, v200
	v_add_f32_e32 v202, v202, v203
	v_add_f32_e32 v204, v204, v205
	v_add_f32_e32 v202, v202, v204
	v_mov_b32_e32 v149, v148
	v_mov_b32_e32 v153, v152
	v_mov_b32_e32 v157, v156
	v_mov_b32_e32 v161, v160
	v_mov_b32_e32 v165, v164
	v_mov_b32_e32 v195, v194
	v_mov_b32_e32 v199, v198
	v_mov_b32_e32 v203, v202
	s_nop 1
	v_permlane16_swap_b32_e32 v148, v149
	v_permlane16_swap_b32_e32 v152, v153
	v_permlane16_swap_b32_e32 v156, v157
	v_permlane16_swap_b32_e32 v160, v161
	v_permlane16_swap_b32_e32 v164, v165
	v_permlane16_swap_b32_e32 v194, v195
	v_permlane16_swap_b32_e32 v198, v199
	v_permlane16_swap_b32_e32 v202, v203
	v_add_f32_e32 v148, v148, v149
	v_add_f32_e32 v152, v152, v153
	v_add_f32_e32 v156, v156, v157
	v_add_f32_e32 v160, v160, v161
	v_add_f32_e32 v164, v164, v165
	v_add_f32_e32 v194, v194, v195
	v_add_f32_e32 v198, v198, v199
	v_add_f32_e32 v202, v202, v203
	v_mov_b32_e32 v149, v148
	v_mov_b32_e32 v153, v152
	v_mov_b32_e32 v157, v156
	v_mov_b32_e32 v161, v160
	v_mov_b32_e32 v165, v164
	v_mov_b32_e32 v195, v194
	v_mov_b32_e32 v199, v198
	v_mov_b32_e32 v203, v202
	s_nop 1
	v_permlane32_swap_b32_e32 v148, v149
	v_permlane32_swap_b32_e32 v152, v153
	v_permlane32_swap_b32_e32 v156, v157
	v_permlane32_swap_b32_e32 v160, v161
	v_permlane32_swap_b32_e32 v164, v165
	v_permlane32_swap_b32_e32 v194, v195
	v_permlane32_swap_b32_e32 v198, v199
	v_permlane32_swap_b32_e32 v202, v203
	v_add_f32_e32 v148, v148, v149
	v_add_f32_e32 v152, v152, v153
	v_add_f32_e32 v156, v156, v157
	v_add_f32_e32 v160, v160, v161
	v_add_f32_e32 v164, v164, v165
	v_add_f32_e32 v194, v194, v195
	v_add_f32_e32 v198, v198, v199
	v_add_f32_e32 v202, v202, v203
	v_fmamk_f32 v148, v148, 0x3a800000, v206
	v_fmamk_f32 v152, v152, 0x3a800000, v206
	v_fmamk_f32 v156, v156, 0x3a800000, v206
	v_fmamk_f32 v160, v160, 0x3a800000, v206
	v_fmamk_f32 v164, v164, 0x3a800000, v206
	v_fmamk_f32 v194, v194, 0x3a800000, v206
	v_fmamk_f32 v198, v198, 0x3a800000, v206
	v_fmamk_f32 v202, v202, 0x3a800000, v206
	v_rsq_f32_e32 v148, v148
	v_rsq_f32_e32 v152, v152
	v_rsq_f32_e32 v156, v156
	v_rsq_f32_e32 v160, v160
	v_rsq_f32_e32 v164, v164
	v_rsq_f32_e32 v194, v194
	v_rsq_f32_e32 v198, v198
	v_rsq_f32_e32 v202, v202
	s_nop 1
	v_pk_mul_f32 v[130:131], v[130:131], v[148:149] op_sel_hi:[1,0]
	v_pk_mul_f32 v[132:133], v[132:133], v[148:149] op_sel_hi:[1,0]
	v_pk_mul_f32 v[134:135], v[134:135], v[148:149] op_sel_hi:[1,0]
	v_pk_mul_f32 v[136:137], v[136:137], v[148:149] op_sel_hi:[1,0]
	v_pk_mul_f32 v[138:139], v[138:139], v[148:149] op_sel_hi:[1,0]
	v_pk_mul_f32 v[140:141], v[140:141], v[148:149] op_sel_hi:[1,0]
	v_pk_mul_f32 v[142:143], v[142:143], v[148:149] op_sel_hi:[1,0]
	v_pk_mul_f32 v[144:145], v[144:145], v[148:149] op_sel_hi:[1,0]
	v_pk_mul_f32 v[114:115], v[114:115], v[152:153] op_sel_hi:[1,0]
	v_pk_mul_f32 v[116:117], v[116:117], v[152:153] op_sel_hi:[1,0]
	v_pk_mul_f32 v[118:119], v[118:119], v[152:153] op_sel_hi:[1,0]
	v_pk_mul_f32 v[120:121], v[120:121], v[152:153] op_sel_hi:[1,0]
	v_pk_mul_f32 v[122:123], v[122:123], v[152:153] op_sel_hi:[1,0]
	v_pk_mul_f32 v[124:125], v[124:125], v[152:153] op_sel_hi:[1,0]
	v_pk_mul_f32 v[126:127], v[126:127], v[152:153] op_sel_hi:[1,0]
	v_pk_mul_f32 v[128:129], v[128:129], v[152:153] op_sel_hi:[1,0]
	v_pk_mul_f32 v[82:83], v[82:83], v[156:157] op_sel_hi:[1,0]
	v_pk_mul_f32 v[84:85], v[84:85], v[156:157] op_sel_hi:[1,0]
	v_pk_mul_f32 v[86:87], v[86:87], v[156:157] op_sel_hi:[1,0]
	v_pk_mul_f32 v[88:89], v[88:89], v[156:157] op_sel_hi:[1,0]
	v_pk_mul_f32 v[102:103], v[102:103], v[156:157] op_sel_hi:[1,0]
	v_pk_mul_f32 v[104:105], v[104:105], v[156:157] op_sel_hi:[1,0]
	v_pk_mul_f32 v[110:111], v[110:111], v[156:157] op_sel_hi:[1,0]
	v_pk_mul_f32 v[112:113], v[112:113], v[156:157] op_sel_hi:[1,0]
	v_pk_mul_f32 v[66:67], v[66:67], v[160:161] op_sel_hi:[1,0]
	v_pk_mul_f32 v[68:69], v[68:69], v[160:161] op_sel_hi:[1,0]
	v_pk_mul_f32 v[70:71], v[70:71], v[160:161] op_sel_hi:[1,0]
	v_pk_mul_f32 v[72:73], v[72:73], v[160:161] op_sel_hi:[1,0]
	v_pk_mul_f32 v[74:75], v[74:75], v[160:161] op_sel_hi:[1,0]
	v_pk_mul_f32 v[76:77], v[76:77], v[160:161] op_sel_hi:[1,0]
	v_pk_mul_f32 v[78:79], v[78:79], v[160:161] op_sel_hi:[1,0]
	v_pk_mul_f32 v[80:81], v[80:81], v[160:161] op_sel_hi:[1,0]
	v_pk_mul_f32 v[50:51], v[50:51], v[164:165] op_sel_hi:[1,0]
	v_pk_mul_f32 v[52:53], v[52:53], v[164:165] op_sel_hi:[1,0]
	v_pk_mul_f32 v[54:55], v[54:55], v[164:165] op_sel_hi:[1,0]
	v_pk_mul_f32 v[56:57], v[56:57], v[164:165] op_sel_hi:[1,0]
	v_pk_mul_f32 v[58:59], v[58:59], v[164:165] op_sel_hi:[1,0]
	v_pk_mul_f32 v[60:61], v[60:61], v[164:165] op_sel_hi:[1,0]
	v_pk_mul_f32 v[62:63], v[62:63], v[164:165] op_sel_hi:[1,0]
	v_pk_mul_f32 v[64:65], v[64:65], v[164:165] op_sel_hi:[1,0]
	v_pk_mul_f32 v[34:35], v[34:35], v[194:195] op_sel_hi:[1,0]
	v_pk_mul_f32 v[36:37], v[36:37], v[194:195] op_sel_hi:[1,0]
	v_pk_mul_f32 v[38:39], v[38:39], v[194:195] op_sel_hi:[1,0]
	v_pk_mul_f32 v[40:41], v[40:41], v[194:195] op_sel_hi:[1,0]
	v_pk_mul_f32 v[42:43], v[42:43], v[194:195] op_sel_hi:[1,0]
	v_pk_mul_f32 v[44:45], v[44:45], v[194:195] op_sel_hi:[1,0]
	v_pk_mul_f32 v[46:47], v[46:47], v[194:195] op_sel_hi:[1,0]
	v_pk_mul_f32 v[48:49], v[48:49], v[194:195] op_sel_hi:[1,0]
	v_pk_mul_f32 v[18:19], v[18:19], v[198:199] op_sel_hi:[1,0]
	v_pk_mul_f32 v[20:21], v[20:21], v[198:199] op_sel_hi:[1,0]
	v_pk_mul_f32 v[22:23], v[22:23], v[198:199] op_sel_hi:[1,0]
	v_pk_mul_f32 v[24:25], v[24:25], v[198:199] op_sel_hi:[1,0]
	v_pk_mul_f32 v[26:27], v[26:27], v[198:199] op_sel_hi:[1,0]
	v_pk_mul_f32 v[28:29], v[28:29], v[198:199] op_sel_hi:[1,0]
	v_pk_mul_f32 v[30:31], v[30:31], v[198:199] op_sel_hi:[1,0]
	v_pk_mul_f32 v[32:33], v[32:33], v[198:199] op_sel_hi:[1,0]
	v_pk_mul_f32 v[2:3], v[2:3], v[202:203] op_sel_hi:[1,0]
	v_pk_mul_f32 v[4:5], v[4:5], v[202:203] op_sel_hi:[1,0]
	v_pk_mul_f32 v[6:7], v[6:7], v[202:203] op_sel_hi:[1,0]
	v_pk_mul_f32 v[8:9], v[8:9], v[202:203] op_sel_hi:[1,0]
	v_pk_mul_f32 v[10:11], v[10:11], v[202:203] op_sel_hi:[1,0]
	v_pk_mul_f32 v[12:13], v[12:13], v[202:203] op_sel_hi:[1,0]
	v_pk_mul_f32 v[14:15], v[14:15], v[202:203] op_sel_hi:[1,0]
	v_pk_mul_f32 v[16:17], v[16:17], v[202:203] op_sel_hi:[1,0]
.Lssd_noscale:
	s_cmp_gt_u32 s70, 29
	s_cbranch_scc0 .LBB0_1245
	v_mov_b32_e32 v146, v1
	v_mov_b32_e32 v90, v189
	s_cmp_lt_i32 s65, 32
	s_mov_b64 s[22:23], 0
	s_cbranch_scc1 .LBB0_1248
	s_sub_i32 s15, s65, 32
	s_lshr_b32 s15, s15, 2
	s_add_i32 s15, s15, 1
	s_mul_hi_u32 s23, s15, 0x1800
	s_mul_i32 s22, s15, 0x1800
